# mLSTM gate/decay scans: 64-lane prefix sums, prefix maxima and wave max via DPP row shifts + row broadcasts + v_readlane instead of 20/26 serial ds_bpermute round trips (f32, add order within the scan
# baseline (speedup 1.0000x reference)
.LBB0_472:
	s_or_b64 exec, exec, s[0:1]
	v_cmp_eq_u32_e64 s[4:5], 0, v104
	s_and_b64 s[0:1], vcc, exec
	s_mov_b32 s0, 0x18800
	s_cselect_b32 s0, s0, 0x18a00
	s_add_i32 s0, s0, 0
	v_lshl_add_u32 v53, v53, 2, s0
	v_add_f32_dpp v57, v57, v57 row_shr:1 row_mask:0xf bank_mask:0xf
	v_add_f32_dpp v51, v51, v51 row_shr:1 row_mask:0xf bank_mask:0xf
	s_nop 0
	v_add_f32_dpp v57, v57, v57 row_shr:2 row_mask:0xf bank_mask:0xf
	v_add_f32_dpp v51, v51, v51 row_shr:2 row_mask:0xf bank_mask:0xf
	s_nop 0
	v_add_f32_dpp v57, v57, v57 row_shr:4 row_mask:0xf bank_mask:0xf
	v_add_f32_dpp v51, v51, v51 row_shr:4 row_mask:0xf bank_mask:0xf
	s_nop 0
	v_add_f32_dpp v57, v57, v57 row_shr:8 row_mask:0xf bank_mask:0xf
	v_add_f32_dpp v51, v51, v51 row_shr:8 row_mask:0xf bank_mask:0xf
	s_nop 0
	v_add_f32_dpp v57, v57, v57 row_bcast:15 row_mask:0xa bank_mask:0xf
	v_add_f32_dpp v51, v51, v51 row_bcast:15 row_mask:0xa bank_mask:0xf
	s_nop 0
	v_add_f32_dpp v57, v57, v57 row_bcast:31 row_mask:0xc bank_mask:0xf
	v_add_f32_dpp v51, v51, v51 row_bcast:31 row_mask:0xc bank_mask:0xf
	s_nop 0
	v_readlane_b32 s8, v57, 63
	s_nop 1
	v_add_f32_e32 v51, s8, v51
	s_nop 0
	v_readlane_b32 s9, v51, 63
	s_nop 1
	v_mov_b32_e32 v50, s9
	v_sub_f32_e32 v57, s9, v57
	v_add_f32_e32 v55, v55, v57
	v_sub_f32_e32 v51, s9, v51
	v_add_f32_e32 v56, v56, v51
	v_max_f32_e32 v51, v55, v56
	s_nop 1
	v_max_f32_dpp v51, v51, v51 row_shr:1 row_mask:0xf bank_mask:0xf
	s_nop 1
	v_max_f32_dpp v51, v51, v51 row_shr:2 row_mask:0xf bank_mask:0xf
	s_nop 1
	v_max_f32_dpp v51, v51, v51 row_shr:4 row_mask:0xf bank_mask:0xf
	s_nop 1
	v_max_f32_dpp v51, v51, v51 row_shr:8 row_mask:0xf bank_mask:0xf
	s_nop 1
	v_max_f32_dpp v51, v51, v51 row_bcast:15 row_mask:0xa bank_mask:0xf
	s_nop 1
	v_max_f32_dpp v51, v51, v51 row_bcast:31 row_mask:0xc bank_mask:0xf
	s_nop 1
	v_readlane_b32 s8, v51, 63
	s_nop 1
	v_mov_b32_e32 v51, s8
	v_sub_f32_e32 v55, v55, v51
	v_mul_f32_e32 v55, 0x3fb8aa3b, v55
	v_sub_f32_e32 v56, v56, v51
	v_exp_f32_e32 v55, v55
	v_mul_f32_e32 v56, 0x3fb8aa3b, v56
	v_exp_f32_e32 v56, v56
	ds_write_b32 v53, v55
	v_lshl_add_u32 v53, v54, 2, s0
	ds_write_b32 v53, v56
	s_and_saveexec_b64 s[0:1], s[4:5]
	s_cbranch_execz .LBB0_474
	s_lshl_b32 s4, s82, 5
	s_lshl_b32 s5, s61, 2
	s_add_i32 s4, s4, s5
	s_or_b32 s4, s4, s31
	s_lshl_b32 s9, s21, 1
	s_lshl_b32 s8, s4, 5
	s_xor_b32 s10, s9, 30
	s_and_b64 s[4:5], vcc, exec
	s_cselect_b32 s4, s9, s10
	s_or_b32 s4, s8, s4
	s_ashr_i32 s5, s4, 31
	s_lshl_b64 s[4:5], s[4:5], 2
	s_add_u32 s4, s16, s4
	s_addc_u32 s5, s17, s5
	global_store_dwordx2 v179, v[50:51], s[4:5] sc1

.LBB0_671:
	s_or_b64 exec, exec, s[0:1]
	v_xor_b32_e32 v35, 63, v171
	v_or_b32_e32 v38, 64, v171
	v_cndmask_b32_e64 v35, v35, v38, s[14:15]
	v_xor_b32_e32 v34, 0x7f, v171
	v_cndmask_b32_e64 v34, v34, v171, s[14:15]
	v_lshl_add_u32 v34, v34, 2, s94
	v_lshl_add_u32 v35, v35, 2, s94
	v_add_f32_dpp v36, v36, v36 row_shr:1 row_mask:0xf bank_mask:0xf
	v_add_f32_dpp v37, v37, v37 row_shr:1 row_mask:0xf bank_mask:0xf
	s_nop 0
	v_add_f32_dpp v36, v36, v36 row_shr:2 row_mask:0xf bank_mask:0xf
	v_add_f32_dpp v37, v37, v37 row_shr:2 row_mask:0xf bank_mask:0xf
	s_nop 0
	v_add_f32_dpp v36, v36, v36 row_shr:4 row_mask:0xf bank_mask:0xf
	v_add_f32_dpp v37, v37, v37 row_shr:4 row_mask:0xf bank_mask:0xf
	s_nop 0
	v_add_f32_dpp v36, v36, v36 row_shr:8 row_mask:0xf bank_mask:0xf
	v_add_f32_dpp v37, v37, v37 row_shr:8 row_mask:0xf bank_mask:0xf
	s_nop 0
	v_add_f32_dpp v36, v36, v36 row_bcast:15 row_mask:0xa bank_mask:0xf
	v_add_f32_dpp v37, v37, v37 row_bcast:15 row_mask:0xa bank_mask:0xf
	s_nop 0
	v_add_f32_dpp v36, v36, v36 row_bcast:31 row_mask:0xc bank_mask:0xf
	v_add_f32_dpp v37, v37, v37 row_bcast:31 row_mask:0xc bank_mask:0xf
	s_nop 0
	v_readlane_b32 s4, v36, 63
	s_nop 1
	v_add_f32_e32 v37, s4, v37
	v_sub_f32_e32 v45, v172, v36
	v_sub_f32_e32 v46, v173, v37
	v_mov_b32_e32 v47, v45
	v_mov_b32_e32 v38, v46
	s_nop 0
	v_max_f32_dpp v47, v47, v47 row_shr:1 row_mask:0xf bank_mask:0xf
	v_max_f32_dpp v38, v38, v38 row_shr:1 row_mask:0xf bank_mask:0xf
	s_nop 0
	v_max_f32_dpp v47, v47, v47 row_shr:2 row_mask:0xf bank_mask:0xf
	v_max_f32_dpp v38, v38, v38 row_shr:2 row_mask:0xf bank_mask:0xf
	s_nop 0
	v_max_f32_dpp v47, v47, v47 row_shr:4 row_mask:0xf bank_mask:0xf
	v_max_f32_dpp v38, v38, v38 row_shr:4 row_mask:0xf bank_mask:0xf
	s_nop 0
	v_max_f32_dpp v47, v47, v47 row_shr:8 row_mask:0xf bank_mask:0xf
	v_max_f32_dpp v38, v38, v38 row_shr:8 row_mask:0xf bank_mask:0xf
	s_nop 0
	v_max_f32_dpp v47, v47, v47 row_bcast:15 row_mask:0xa bank_mask:0xf
	v_max_f32_dpp v38, v38, v38 row_bcast:15 row_mask:0xa bank_mask:0xf
	s_nop 0
	v_max_f32_dpp v47, v47, v47 row_bcast:31 row_mask:0xc bank_mask:0xf
	v_max_f32_dpp v38, v38, v38 row_bcast:31 row_mask:0xc bank_mask:0xf
	s_nop 0
	v_readlane_b32 s4, v47, 63
	s_nop 1
	v_max_f32_e32 v38, s4, v38
	ds_write2st64_b32 v34, v36, v45 offset1:2
	ds_write2st64_b32 v35, v37, v46 offset1:2
	ds_write_b32 v34, v47 offset:1024
	ds_write_b32 v35, v38 offset:1024

.LBB0_1393:
	s_endpgm
	s_nop 0
	s_nop 0
	s_nop 0
	s_nop 0
	s_nop 0
	s_nop 0
	s_nop 0
	s_nop 0
	s_nop 0
	s_nop 0
	s_nop 0
	s_nop 0
	s_nop 0
	s_nop 0
	s_nop 0
	s_nop 0
	s_nop 0
	s_nop 0
	s_nop 0
	s_nop 0
	s_nop 0
	s_nop 0
	s_nop 0
	s_nop 0
	s_nop 0
	s_nop 0
	s_nop 0
	s_nop 0
	s_nop 0
	s_nop 0
	s_nop 0
	s_nop 0
	s_nop 0
	s_nop 0
	s_nop 0
	s_nop 0
	s_nop 0
	s_nop 0
	s_nop 0
	s_nop 0
	s_nop 0
	s_nop 0
	s_nop 0
	s_nop 0
	s_nop 0
	s_nop 0
	s_nop 0
	s_nop 0
	s_nop 0
	s_nop 0
	s_nop 0
	s_nop 0
	s_nop 0
	s_nop 0
	s_nop 0
	s_nop 0
	s_nop 0
	s_nop 0
	s_nop 0
	s_nop 0
	s_nop 0
	s_nop 0
	s_nop 0
	s_nop 0
	s_nop 0
	s_nop 0
	s_nop 0
	s_nop 0
	s_nop 0
	s_nop 0
	s_nop 0
	s_nop 0
	s_nop 0
	s_nop 0
	s_nop 0
	s_nop 0
	s_nop 0
	s_nop 0
	s_nop 0
	s_nop 0
	s_nop 0
	s_nop 0
	s_nop 0
	s_nop 0
	s_nop 0
	s_nop 0
	s_nop 0
	s_nop 0
	s_nop 0
	s_nop 0
	s_nop 0
	s_nop 0
	s_nop 0
	s_nop 0
	s_nop 0
	s_nop 0
	s_nop 0
	s_nop 0
	s_nop 0
	s_nop 0
	s_nop 0
	s_nop 0
	s_nop 0
	s_nop 0
	s_nop 0
	s_nop 0
	s_nop 0
	s_nop 0
	s_nop 0
	s_nop 0
	s_nop 0
	s_nop 0
	s_nop 0
	s_nop 0
	s_nop 0
	s_nop 0
	s_nop 0
	s_nop 0
	s_nop 0
	s_nop 0
	s_nop 0
	s_nop 0
	s_nop 0
	s_nop 0
	s_nop 0
	s_nop 0
	s_nop 0
	s_nop 0
	s_nop 0
	s_nop 0
	s_nop 0
	s_nop 0
	s_nop 0
	s_nop 0
	s_nop 0
	s_nop 0
	s_nop 0
	s_nop 0
	s_nop 0
	s_nop 0
	s_nop 0
	s_nop 0
	s_nop 0
	s_nop 0
	s_nop 0
	s_nop 0
	s_nop 0
	s_nop 0
	s_nop 0
	s_nop 0
	s_nop 0
	s_nop 0
	s_nop 0
	s_nop 0
	s_nop 0
	s_nop 0
	s_nop 0
	s_nop 0
	s_nop 0
	s_nop 0
	s_nop 0
	s_nop 0
	s_nop 0
	s_nop 0
	s_nop 0
	s_nop 0
	s_nop 0
	s_nop 0
	s_nop 0
	s_nop 0
	s_nop 0
	s_nop 0
	s_nop 0
	s_nop 0
	s_nop 0
	s_nop 0
	s_nop 0
	s_nop 0
	s_nop 0
	s_nop 0
	s_nop 0
	s_nop 0
	s_nop 0
	s_nop 0
	s_nop 0
	s_nop 0
	s_nop 0
	s_nop 0
	s_nop 0
	s_nop 0
	s_nop 0
	s_nop 0
	s_nop 0
	s_nop 0
	s_nop 0
	s_nop 0
	s_nop 0
	s_nop 0
	s_nop 0
	s_nop 0
	s_nop 0
	s_nop 0
	s_nop 0
	s_nop 0
	s_nop 0
	s_nop 0
	s_nop 0
	s_nop 0
	s_nop 0
	s_nop 0
	s_nop 0
	s_nop 0
	s_nop 0
	s_nop 0
	s_nop 0
	s_nop 0
	s_nop 0
	s_nop 0
	s_nop 0
	s_nop 0
	s_nop 0
	s_nop 0
	s_nop 0
	s_nop 0
	s_nop 0
	s_nop 0
	s_nop 0
	s_nop 0
	s_nop 0
	s_nop 0
	s_nop 0
	s_nop 0
	s_nop 0
	s_nop 0
	s_nop 0
	s_nop 0
	s_nop 0
	s_nop 0
	s_nop 0
	s_nop 0
	s_nop 0
	s_nop 0
	s_nop 0
	s_nop 0
	s_nop 0
	s_nop 0
	s_nop 0
	s_nop 0
	s_nop 0
	s_nop 0
	s_nop 0
	s_nop 0
	s_nop 0
	s_nop 0
	s_nop 0
	s_nop 0
	s_nop 0
	s_nop 0
	s_nop 0
	s_nop 0
	s_nop 0
	s_nop 0
	s_nop 0
	s_nop 0
	s_nop 0
	s_nop 0
	s_nop 0
	s_nop 0
	s_nop 0
	s_nop 0
	s_nop 0
	s_nop 0
	s_nop 0
	s_nop 0
	s_nop 0
	s_nop 0
	s_nop 0
	s_nop 0
	s_nop 0
	s_nop 0
	s_nop 0
	s_nop 0
	s_nop 0
	s_nop 0
	s_nop 0
	s_nop 0
	s_nop 0
	s_nop 0
	s_nop 0
	s_nop 0
	s_nop 0
	s_nop 0
	s_nop 0
	s_nop 0
	s_nop 0
	s_nop 0
	s_nop 0
	s_nop 0
	s_nop 0
	s_nop 0
	s_nop 0
	s_nop 0
	s_nop 0
	s_nop 0
	s_nop 0
	s_nop 0
	s_nop 0
	s_nop 0
	s_nop 0
	s_nop 0
	s_nop 0
	s_nop 0
	s_nop 0
	s_nop 0
	s_nop 0
	s_nop 0
	s_nop 0
	s_nop 0
	s_nop 0
	s_nop 0
	s_nop 0
	s_nop 0
	s_nop 0
	s_nop 0
	s_nop 0
	s_nop 0
	s_nop 0
	s_nop 0
	s_nop 0
	s_nop 0
	s_nop 0
	s_nop 0
	s_nop 0
	s_nop 0
	s_nop 0
	s_nop 0
	s_nop 0
	s_nop 0
	s_nop 0
	s_nop 0
	s_nop 0
	s_nop 0
	s_nop 0
	s_nop 0
	s_nop 0
	s_nop 0
	s_nop 0
	s_nop 0
	s_nop 0
	s_nop 0
	s_nop 0
	s_nop 0
	s_nop 0
	s_nop 0
	s_nop 0
	s_nop 0
	s_nop 0
	s_nop 0
	s_nop 0
	s_nop 0
	s_nop 0
	s_nop 0
	s_nop 0
	s_nop 0
	s_nop 0
	s_nop 0
	s_nop 0
	s_nop 0
	s_nop 0
	s_nop 0
	s_nop 0
	s_nop 0
	s_nop 0
	s_nop 0
	s_nop 0
	s_nop 0
	s_nop 0
	s_nop 0
	s_nop 0
	s_nop 0
	s_nop 0
	s_nop 0
	s_nop 0
	s_nop 0
	s_nop 0
	s_nop 0
	s_nop 0
	s_nop 0
	s_nop 0
	s_nop 0
	s_nop 0
	s_nop 0
	s_nop 0
	s_nop 0
	s_nop 0
	s_nop 0
	s_nop 0
	s_nop 0
	s_nop 0
	s_nop 0
	s_nop 0
	s_nop 0
	s_nop 0
	s_nop 0
	s_nop 0
	s_nop 0
	s_nop 0
	s_nop 0
	s_nop 0
	s_nop 0
	s_nop 0
	s_nop 0
	s_nop 0
	s_nop 0
	s_nop 0
	s_endpgm
